# v44 + nt on the 5 once-read RG-LRU stream loads (protect attention K/V in L2 during the mixed phase)
# baseline (speedup 1.0000x reference)
; __device__ __forceinline__ void rg_item(LAS unsigned char* lds, int item, const bf16* __restrict__ proj, bf16* __restrict__ mix, const bf16* __restrict__ Gt, ...
;     ...
;     { const bf16* xg = proj + rowbase * INW + 64 * g; v4u rawv[5];
; #pragma unroll
;       for (int i5 = 0; i5 < 5; ++i5) { const int c = tid + 512 * i5, r = c >> 3, t = t0 - 3 + r; rawv[i5] = (v4u){0u, 0u, 0u, 0u};
;           if (c < 259 * 8 && t >= 0) rawv[i5] = *(const v4u*)(xg + (size_t)t * INW + (c & 7) * 8); }
.LBB0_111:
	s_ashr_i32 s6, s97, 6
	s_bfe_u32 s31, s97, 0x20004
	s_and_b32 s5, s97, 15
	s_lshl_b32 s4, s6, 8
	s_mul_i32 s0, s31, 0x1400000
	v_readlane_b32 s8, v252, 4
	v_readlane_b32 s9, v252, 5
	s_add_u32 s0, s8, s0
	s_addc_u32 s1, s9, 0
	s_lshl_b32 s7, s5, 7
	s_add_u32 s0, s0, s7
	s_addc_u32 s1, s1, 0
	s_add_i32 s7, s4, -3
	v_add_u32_e32 v4, s7, v114
	v_cmp_lt_i32_e32 vcc, -1, v4
	v_lshl_add_u64 v[106:107], s[0:1], 0, v[84:85]
	s_and_b64 s[8:9], s[36:37], vcc
	v_mov_b32_e32 v0, 0
	v_mov_b32_e32 v1, 0
	v_mov_b32_e32 v2, 0
	v_mov_b32_e32 v3, 0
	s_and_saveexec_b64 s[0:1], s[8:9]
	s_cbranch_execz .LBB0_113
	s_movk_i32 s8, 0x2800
	v_mad_u64_u32 v[0:1], s[8:9], v4, s8, v[106:107]
	global_load_dwordx4 v[0:3], v[0:1], off nt
.LBB0_113:
	s_or_b64 exec, exec, s[0:1]
	v_add_u32_e32 v8, s7, v112
	v_cmp_lt_i32_e32 vcc, -1, v8
	v_mov_b32_e32 v4, v85
	v_mov_b32_e32 v5, v85
	v_mov_b32_e32 v6, v85
	v_mov_b32_e32 v7, v85
	s_waitcnt vmcnt(0)
	v_mov_b32_e32 v52, v0
	v_mov_b32_e32 v53, v1
	v_mov_b32_e32 v54, v2
	v_mov_b32_e32 v55, v3
	v_mov_b32_e32 v56, v85
	v_mov_b32_e32 v57, v85
	v_mov_b32_e32 v58, v85
	v_mov_b32_e32 v59, v85
	v_mov_b32_e32 v60, v85
	v_mov_b32_e32 v61, v85
	v_mov_b32_e32 v62, v85
	v_mov_b32_e32 v63, v85
	v_mov_b32_e32 v36, v0
	v_mov_b32_e32 v37, v1
	v_mov_b32_e32 v38, v2
	v_mov_b32_e32 v39, v3
	v_mov_b32_e32 v40, v85
	v_mov_b32_e32 v41, v85
	v_mov_b32_e32 v42, v85
	v_mov_b32_e32 v43, v85
	v_mov_b32_e32 v44, v85
	v_mov_b32_e32 v45, v85
	v_mov_b32_e32 v46, v85
	v_mov_b32_e32 v47, v85
	v_mov_b32_e32 v48, v85
	v_mov_b32_e32 v49, v85
	v_mov_b32_e32 v50, v85
	v_mov_b32_e32 v51, v85
	v_mov_b32_e32 v16, v0
	v_mov_b32_e32 v17, v1
	v_mov_b32_e32 v18, v2
	v_mov_b32_e32 v19, v3
	v_mov_b32_e32 v20, v85
	v_mov_b32_e32 v21, v85
	v_mov_b32_e32 v22, v85
	v_mov_b32_e32 v23, v85
	v_mov_b32_e32 v24, v85
	v_mov_b32_e32 v25, v85
	v_mov_b32_e32 v26, v85
	v_mov_b32_e32 v27, v85
	v_mov_b32_e32 v28, v85
	v_mov_b32_e32 v29, v85
	v_mov_b32_e32 v30, v85
	v_mov_b32_e32 v31, v85
	v_mov_b32_e32 v32, v85
	v_mov_b32_e32 v33, v85
	v_mov_b32_e32 v34, v85
	v_mov_b32_e32 v35, v85
	s_and_b64 s[8:9], s[38:39], vcc
	s_and_saveexec_b64 s[0:1], s[8:9]
	s_movk_i32 s14, 0x3000
	s_cbranch_execz .LBB0_115
	s_movk_i32 s8, 0x2800
	v_mad_u64_u32 v[4:5], s[8:9], v8, s8, v[106:107]
	global_load_dwordx4 v[4:7], v[4:5], off nt
	v_mov_b32_e32 v30, v85
	v_mov_b32_e32 v31, v85
	v_mov_b32_e32 v8, v85
	v_mov_b32_e32 v9, v85
	v_mov_b32_e32 v10, v85
	v_mov_b32_e32 v11, v85
	v_mov_b32_e32 v16, v0
	v_mov_b32_e32 v17, v1
	v_mov_b32_e32 v18, v2
	v_mov_b32_e32 v19, v3
	v_mov_b32_e32 v24, v85
	v_mov_b32_e32 v25, v85
	v_mov_b32_e32 v26, v85
	v_mov_b32_e32 v27, v85
	v_mov_b32_e32 v28, v85
	v_mov_b32_e32 v29, v85
	v_mov_b32_e32 v36, v0
	v_mov_b32_e32 v37, v1
	v_mov_b32_e32 v38, v2
	v_mov_b32_e32 v39, v3
	v_mov_b32_e32 v44, v85
	v_mov_b32_e32 v45, v85
	v_mov_b32_e32 v46, v85
	v_mov_b32_e32 v47, v85
	v_mov_b32_e32 v48, v85
	v_mov_b32_e32 v49, v85
	v_mov_b32_e32 v50, v85
	v_mov_b32_e32 v51, v85
	v_mov_b32_e32 v32, v85
	v_mov_b32_e32 v33, v85
	v_mov_b32_e32 v34, v85
	v_mov_b32_e32 v35, v85
	s_waitcnt vmcnt(0)
	v_mov_b32_e32 v20, v4
	v_mov_b32_e32 v21, v5
	v_mov_b32_e32 v22, v6
	v_mov_b32_e32 v23, v7
	v_mov_b64_e32 v[82:83], v[30:31]
	v_mov_b32_e32 v40, v4
	v_mov_b32_e32 v41, v5
	v_mov_b32_e32 v42, v6
	v_mov_b32_e32 v43, v7
	v_mov_b64_e32 v[62:63], v[10:11]
	v_mov_b64_e32 v[60:61], v[8:9]
	v_mov_b64_e32 v[58:59], v[6:7]
	v_mov_b64_e32 v[56:57], v[4:5]
	v_mov_b64_e32 v[54:55], v[2:3]
	v_mov_b64_e32 v[52:53], v[0:1]
	v_mov_b64_e32 v[80:81], v[28:29]
	v_mov_b64_e32 v[78:79], v[26:27]
	v_mov_b64_e32 v[76:77], v[24:25]
	v_mov_b64_e32 v[74:75], v[22:23]
	v_mov_b64_e32 v[72:73], v[20:21]
	v_mov_b64_e32 v[70:71], v[18:19]
	v_mov_b64_e32 v[68:69], v[16:17]
	v_mov_b64_e32 v[66:67], v[14:15]
	v_mov_b64_e32 v[64:65], v[12:13]
; __device__ __forceinline__ void rg_item(LAS unsigned char* lds, int item, const bf16* __restrict__ proj, bf16* __restrict__ mix, const bf16* __restrict__ Gt, ...
;     ...
;     { const bf16* xg = proj + rowbase * INW + 64 * g; v4u rawv[5];
; #pragma unroll
;       for (int i5 = 0; i5 < 5; ++i5) { const int c = tid + 512 * i5, r = c >> 3, t = t0 - 3 + r; rawv[i5] = (v4u){0u, 0u, 0u, 0u};
;           if (c < 259 * 8 && t >= 0) rawv[i5] = *(const v4u*)(xg + (size_t)t * INW + (c & 7) * 8); }
.LBB0_115:
	s_or_b64 exec, exec, s[0:1]
	v_add_u32_e32 v8, s7, v113
	v_cmp_lt_i32_e32 vcc, -1, v8
	s_and_b64 s[8:9], s[40:41], vcc
	s_and_saveexec_b64 s[0:1], s[8:9]
	s_cbranch_execz .LBB0_117
	s_movk_i32 s8, 0x2800
	v_mad_u64_u32 v[8:9], s[8:9], v8, s8, v[106:107]
	global_load_dwordx4 v[8:11], v[8:9], off nt
	v_mov_b32_e32 v30, v85
	v_mov_b32_e32 v31, v85
	v_mov_b32_e32 v12, v85
	v_mov_b32_e32 v13, v85
	v_mov_b32_e32 v14, v85
	v_mov_b32_e32 v15, v85
	v_mov_b32_e32 v16, v0
	v_mov_b32_e32 v17, v1
	v_mov_b32_e32 v18, v2
	v_mov_b32_e32 v19, v3
	v_mov_b32_e32 v20, v4
	v_mov_b32_e32 v21, v5
	v_mov_b32_e32 v22, v6
	v_mov_b32_e32 v23, v7
	v_mov_b32_e32 v28, v85
	v_mov_b32_e32 v29, v85
	v_mov_b32_e32 v32, v85
	v_mov_b32_e32 v33, v85
	v_mov_b32_e32 v34, v85
	v_mov_b32_e32 v35, v85
	s_waitcnt vmcnt(0)
	v_mov_b32_e32 v24, v8
	v_mov_b32_e32 v25, v9
	v_mov_b32_e32 v26, v10
	v_mov_b32_e32 v27, v11
	v_mov_b64_e32 v[66:67], v[30:31]
	v_mov_b64_e32 v[64:65], v[28:29]
	v_mov_b64_e32 v[62:63], v[26:27]
	v_mov_b64_e32 v[60:61], v[24:25]
	v_mov_b64_e32 v[58:59], v[22:23]
	v_mov_b64_e32 v[56:57], v[20:21]
	v_mov_b64_e32 v[54:55], v[18:19]
	v_mov_b64_e32 v[52:53], v[16:17]
	v_mov_b64_e32 v[82:83], v[30:31]
	v_mov_b64_e32 v[50:51], v[14:15]
	v_mov_b64_e32 v[48:49], v[12:13]
	v_mov_b64_e32 v[46:47], v[10:11]
	v_mov_b64_e32 v[44:45], v[8:9]
	v_mov_b64_e32 v[42:43], v[6:7]
	v_mov_b64_e32 v[40:41], v[4:5]
	v_mov_b64_e32 v[38:39], v[2:3]
	v_mov_b64_e32 v[36:37], v[0:1]
	v_mov_b64_e32 v[62:63], v[10:11]
	v_mov_b64_e32 v[60:61], v[8:9]
	v_mov_b64_e32 v[58:59], v[6:7]
	v_mov_b64_e32 v[56:57], v[4:5]
	v_mov_b64_e32 v[54:55], v[2:3]
	v_mov_b64_e32 v[52:53], v[0:1]
	v_mov_b64_e32 v[80:81], v[28:29]
	v_mov_b64_e32 v[78:79], v[26:27]
	v_mov_b64_e32 v[76:77], v[24:25]
	v_mov_b64_e32 v[74:75], v[22:23]
	v_mov_b64_e32 v[72:73], v[20:21]
	v_mov_b64_e32 v[70:71], v[18:19]
	v_mov_b64_e32 v[68:69], v[16:17]
	v_mov_b64_e32 v[66:67], v[14:15]
	v_mov_b64_e32 v[64:65], v[12:13]
.LBB0_117:
	s_or_b64 exec, exec, s[0:1]
	v_add_u32_e32 v0, s7, v115
	v_cmp_lt_i32_e32 vcc, -1, v0
	s_and_b64 s[8:9], s[42:43], vcc
	s_and_saveexec_b64 s[0:1], s[8:9]
	s_cbranch_execz .LBB0_119
	s_movk_i32 s8, 0x2800
	v_mad_u64_u32 v[0:1], s[8:9], v0, s8, v[106:107]
	global_load_dwordx4 v[64:67], v[0:1], off nt
	v_mov_b32_e32 v68, v85
	v_mov_b32_e32 v69, v85
	v_mov_b32_e32 v70, v85
	v_mov_b32_e32 v71, v85
	s_waitcnt vmcnt(0)
	v_mov_b64_e32 v[16:17], v[52:53]
	v_mov_b64_e32 v[36:37], v[72:73]
	v_mov_b64_e32 v[38:39], v[74:75]
	v_mov_b64_e32 v[40:41], v[76:77]
	v_mov_b64_e32 v[42:43], v[78:79]
	v_mov_b64_e32 v[44:45], v[80:81]
	v_mov_b64_e32 v[46:47], v[82:83]
	v_mov_b64_e32 v[18:19], v[54:55]
	v_mov_b64_e32 v[20:21], v[56:57]
	v_mov_b64_e32 v[22:23], v[58:59]
	v_mov_b64_e32 v[24:25], v[60:61]
	v_mov_b64_e32 v[26:27], v[62:63]
	v_mov_b64_e32 v[32:33], v[68:69]
	v_mov_b64_e32 v[34:35], v[70:71]
	v_mov_b64_e32 v[28:29], v[64:65]
	v_mov_b64_e32 v[30:31], v[66:67]
	v_mov_b64_e32 v[36:37], v[52:53]
	v_mov_b64_e32 v[38:39], v[54:55]
	v_mov_b64_e32 v[40:41], v[56:57]
	v_mov_b64_e32 v[42:43], v[58:59]
	v_mov_b64_e32 v[44:45], v[60:61]
	v_mov_b64_e32 v[46:47], v[62:63]
	v_mov_b64_e32 v[48:49], v[64:65]
	v_mov_b64_e32 v[50:51], v[66:67]
	v_mov_b64_e32 v[52:53], v[68:69]
	v_mov_b64_e32 v[54:55], v[70:71]
	v_mov_b64_e32 v[56:57], v[72:73]
	v_mov_b64_e32 v[58:59], v[74:75]
	v_mov_b64_e32 v[60:61], v[76:77]
	v_mov_b64_e32 v[62:63], v[78:79]
	v_mov_b64_e32 v[64:65], v[80:81]
	v_mov_b64_e32 v[66:67], v[82:83]
.LBB0_119:
	s_or_b64 exec, exec, s[0:1]
	v_add_u32_e32 v0, s7, v120
	v_cmp_lt_i32_e32 vcc, -1, v0
	s_and_b64 s[8:9], s[44:45], vcc
	s_and_saveexec_b64 s[0:1], s[8:9]
	s_cbranch_execz .LBB0_121
	s_movk_i32 s7, 0x2800
	v_mad_u64_u32 v[0:1], s[8:9], v0, s7, v[106:107]
	global_load_dwordx4 v[52:55], v[0:1], off nt
	s_waitcnt vmcnt(0)
	v_mov_b64_e32 v[16:17], v[36:37]
	v_mov_b64_e32 v[18:19], v[38:39]
	v_mov_b64_e32 v[20:21], v[40:41]
	v_mov_b64_e32 v[22:23], v[42:43]
	v_mov_b64_e32 v[24:25], v[44:45]
	v_mov_b64_e32 v[26:27], v[46:47]
	v_mov_b64_e32 v[28:29], v[48:49]
	v_mov_b64_e32 v[30:31], v[50:51]
	v_mov_b64_e32 v[32:33], v[52:53]
	v_mov_b64_e32 v[34:35], v[54:55]
	v_mov_b64_e32 v[36:37], v[56:57]
	v_mov_b64_e32 v[38:39], v[58:59]
	v_mov_b64_e32 v[40:41], v[60:61]
	v_mov_b64_e32 v[42:43], v[62:63]
	v_mov_b64_e32 v[44:45], v[64:65]
	v_mov_b64_e32 v[46:47], v[66:67]
